# u9 plus in-proj/out-proj loop first half: the five MFMAs hipcc interleaved into the staging section moved ahead of it (pure MFMA stretch then pure staging)
# baseline (speedup 1.0000x reference)
; DI void gemm_128_deep(const bf16_t* __restrict__ A, int lda, const bf16_t* __restrict__ B, int ldb, int K, f32x16 (&acc)[2][2], bf16_t* sA, bf16_t* sBunused) {
;     ...
;   for (int k0 = 0; k0 < K - 256; k0 += 128) {
;     MMA_TILE(0)
;     ST_LDS(1, qa0, qa1, qa2, qa3, qb0, qb1, qb2, qb3)
;     GL_Q(k0 + 192)
;     __syncthreads();
;     MMA_TILE(1)
;     ST_LDS(0, pa0, pa1, pa2, pa3, pb0, pb1, pb2, pb3)
;     GL_P(k0 + 256)
;     __syncthreads();
;   }
.LBB0_208:
	ds_read_b128 v[168:171], v128
	ds_read_b128 v[172:175], v129 offset:18432
	ds_read_b128 v[176:179], v128 offset:32
	ds_read_b128 v[180:183], v129 offset:18464
	ds_read_b128 v[184:187], v129 offset:23040
	ds_read_b128 v[188:191], v129 offset:23072
	s_mov_b32 s45, 0x1304000
	s_waitcnt lgkmcnt(4)
	v_mfma_f32_32x32x16_bf16 v[48:63], v[168:171], v[172:175], v[48:63]
	s_mov_b32 s46, 0x1324000
	s_mov_b32 s47, 0x1344000
	s_mov_b32 s48, 0x1364000
	s_addk_i32 s43, 0x80
	s_cmpk_lt_u32 s43, 0x680
	s_waitcnt lgkmcnt(1)
	v_mfma_f32_32x32x16_bf16 v[32:47], v[168:171], v[184:187], v[32:47]
	ds_read_b128 v[168:171], v128 offset:4608
	ds_read_b128 v[192:195], v128 offset:4640
	s_waitcnt lgkmcnt(1)
	v_mfma_f32_32x32x16_bf16 v[16:31], v[168:171], v[172:175], v[16:31]
	v_mfma_f32_32x32x16_bf16 v[0:15], v[168:171], v[184:187], v[0:15]
	v_mfma_f32_32x32x16_bf16 v[48:63], v[176:179], v[180:183], v[48:63]
	v_mfma_f32_32x32x16_bf16 v[32:47], v[176:179], v[188:191], v[32:47]
	s_waitcnt lgkmcnt(0)
	v_mfma_f32_32x32x16_bf16 v[16:31], v[192:195], v[180:183], v[16:31]
	ds_read_b128 v[168:171], v129 offset:18496
	ds_read_b128 v[172:175], v128 offset:64
	ds_read_b128 v[176:179], v128 offset:96
	ds_read_b128 v[180:183], v128 offset:4672
	ds_read_b128 v[184:187], v128 offset:4704
	v_mfma_f32_32x32x16_bf16 v[0:15], v[192:195], v[188:191], v[0:15]
	ds_read_b128 v[188:191], v129 offset:18528
	ds_read_b128 v[192:195], v129 offset:23104
	ds_read_b128 v[196:199], v129 offset:23136
	s_waitcnt lgkmcnt(6)
	v_mfma_f32_32x32x16_bf16 v[48:63], v[172:175], v[168:171], v[48:63]
	s_waitcnt lgkmcnt(1)
	v_mfma_f32_32x32x16_bf16 v[32:47], v[172:175], v[192:195], v[32:47]
	v_mfma_f32_32x32x16_bf16 v[16:31], v[180:183], v[168:171], v[16:31]
	v_mfma_f32_32x32x16_bf16 v[0:15], v[180:183], v[192:195], v[0:15]
	v_mfma_f32_32x32x16_bf16 v[48:63], v[176:179], v[188:191], v[48:63]
	s_setprio 0
	s_waitcnt vmcnt(15)
	ds_write_b128 v130, v[96:99] offset:36864
	s_waitcnt vmcnt(14)
	ds_write_b128 v130, v[100:103] offset:41472
	s_waitcnt vmcnt(13)
	ds_write_b128 v130, v[104:107] offset:46080
	s_waitcnt vmcnt(12)
	ds_write_b128 v130, v[108:111] offset:50688
	v_lshl_add_u64 v[96:97], v[150:151], 0, v[156:157]
	v_add_co_u32_e32 v152, vcc, s83, v96
	v_lshl_add_u64 v[98:99], v[148:149], 0, v[156:157]
	s_nop 0
	v_addc_co_u32_e32 v153, vcc, 0, v97, vcc
	v_add_co_u32_e32 v200, vcc, s84, v96
	s_nop 1
	v_addc_co_u32_e32 v201, vcc, 0, v97, vcc
	v_add_co_u32_e32 v202, vcc, s85, v96
	s_waitcnt vmcnt(11)
	ds_write_b128 v130, v[112:115] offset:55296
	s_waitcnt vmcnt(10)
	ds_write_b128 v130, v[116:119] offset:59904
	s_waitcnt vmcnt(9)
	ds_write_b128 v130, v[120:123] offset:64512
	s_waitcnt vmcnt(8)
	ds_write_b128 v131, v[124:127] offset:13824
	v_addc_co_u32_e32 v203, vcc, 0, v97, vcc
	v_add_co_u32_e32 v204, vcc, s86, v96
	v_lshl_add_u64 v[148:149], v[148:149], 0, s[94:95]
	s_nop 0
	v_addc_co_u32_e32 v205, vcc, 0, v97, vcc
	v_add_co_u32_e32 v206, vcc, s45, v98
	s_nop 0
	s_nop 0
	v_addc_co_u32_e32 v207, vcc, 0, v99, vcc
	v_add_co_u32_e32 v208, vcc, s46, v98
	v_lshl_add_u64 v[150:151], v[150:151], 0, s[94:95]
	s_nop 0
	v_addc_co_u32_e32 v209, vcc, 0, v99, vcc
	v_add_co_u32_e32 v210, vcc, s47, v98
	s_nop 1
	s_nop 0
	v_addc_co_u32_e32 v211, vcc, 0, v99, vcc
	v_add_co_u32_e32 v212, vcc, s48, v98
	s_nop 0
	s_nop 0
	v_addc_co_u32_e32 v213, vcc, 0, v99, vcc
	global_load_dwordx4 v[96:99], v[152:153], off offset:2176
	global_load_dwordx4 v[100:103], v[200:201], off offset:2176
	global_load_dwordx4 v[104:107], v[202:203], off offset:2176
	global_load_dwordx4 v[108:111], v[204:205], off offset:2176
	global_load_dwordx4 v[112:115], v[206:207], off offset:2176
	global_load_dwordx4 v[116:119], v[208:209], off offset:2176
	global_load_dwordx4 v[120:123], v[210:211], off offset:2176
	global_load_dwordx4 v[124:127], v[212:213], off offset:2176
	s_waitcnt lgkmcnt(0)
	s_barrier
	s_setprio 1
	v_mfma_f32_32x32x16_bf16 v[32:47], v[176:179], v[196:199], v[32:47]
	ds_read_b128 v[168:171], v128 offset:36864
	ds_read_b128 v[172:175], v129 offset:55296
	ds_read_b128 v[176:179], v128 offset:36896
	ds_read_b128 v[180:183], v129 offset:55328
	v_mfma_f32_32x32x16_bf16 v[16:31], v[184:187], v[188:191], v[16:31]
	v_mfma_f32_32x32x16_bf16 v[0:15], v[184:187], v[196:199], v[0:15]
	ds_read_b128 v[184:187], v129 offset:59904
	ds_read_b128 v[188:191], v129 offset:59936
	s_waitcnt lgkmcnt(4)
	v_mfma_f32_32x32x16_bf16 v[48:63], v[168:171], v[172:175], v[48:63]
	s_waitcnt lgkmcnt(1)
	v_mfma_f32_32x32x16_bf16 v[32:47], v[168:171], v[184:187], v[32:47]
	ds_read_b128 v[168:171], v128 offset:41472
	ds_read_b128 v[192:195], v128 offset:41504
	s_waitcnt lgkmcnt(1)
	v_mfma_f32_32x32x16_bf16 v[16:31], v[168:171], v[172:175], v[16:31]
	v_mfma_f32_32x32x16_bf16 v[0:15], v[168:171], v[184:187], v[0:15]
	v_mfma_f32_32x32x16_bf16 v[48:63], v[176:179], v[180:183], v[48:63]
	v_mfma_f32_32x32x16_bf16 v[32:47], v[176:179], v[188:191], v[32:47]
	s_waitcnt lgkmcnt(0)
	v_mfma_f32_32x32x16_bf16 v[16:31], v[192:195], v[180:183], v[16:31]
	ds_read_b128 v[168:171], v128 offset:36928
	ds_read_b128 v[172:175], v129 offset:55360
	ds_read_b128 v[176:179], v128 offset:36960
	ds_read_b128 v[180:183], v129 offset:55392
	v_mfma_f32_32x32x16_bf16 v[0:15], v[192:195], v[188:191], v[0:15]
	ds_read_b128 v[184:187], v129 offset:59968
	ds_read_b128 v[188:191], v129 offset:60000
	s_waitcnt lgkmcnt(4)
	v_mfma_f32_32x32x16_bf16 v[48:63], v[168:171], v[172:175], v[48:63]
	s_waitcnt lgkmcnt(1)
	v_mfma_f32_32x32x16_bf16 v[32:47], v[168:171], v[184:187], v[32:47]
	ds_read_b128 v[168:171], v128 offset:41536
	ds_read_b128 v[192:195], v128 offset:41568
	s_setprio 0
	s_waitcnt vmcnt(13)
	ds_write_b128 v130, v[92:95]
	ds_write_b128 v130, v[64:67] offset:4608
	ds_write_b128 v130, v[68:71] offset:9216
	s_waitcnt vmcnt(11)
	ds_write_b128 v130, v[84:87] offset:13824
	ds_write_b128 v130, v[72:75] offset:18432
	s_waitcnt vmcnt(10)
	ds_write_b128 v130, v[76:79] offset:23040
	s_waitcnt vmcnt(9)
	ds_write_b128 v130, v[80:83] offset:27648
	s_waitcnt vmcnt(8)
	ds_write_b128 v130, v[88:91] offset:32256
	global_load_dwordx4 v[92:95], v[152:153], off offset:2304
	global_load_dwordx4 v[64:67], v[200:201], off offset:2304
	global_load_dwordx4 v[68:71], v[202:203], off offset:2304
	global_load_dwordx4 v[84:87], v[204:205], off offset:2304
	global_load_dwordx4 v[72:75], v[206:207], off offset:2304
	global_load_dwordx4 v[76:79], v[208:209], off offset:2304
	global_load_dwordx4 v[80:83], v[210:211], off offset:2304
	global_load_dwordx4 v[88:91], v[212:213], off offset:2304
	s_waitcnt lgkmcnt(0)
	s_barrier
; DI void gemm_128_deep(const bf16_t* __restrict__ A, int lda, const bf16_t* __restrict__ B, int ldb, int K, f32x16 (&acc)[2][2], bf16_t* sA, bf16_t* sBunused) {
;     ...
;   for (int k0 = 0; k0 < K - 256; k0 += 128) {
;     MMA_TILE(0)
;     ST_LDS(1, qa0, qa1, qa2, qa3, qb0, qb1, qb2, qb3)
;     GL_Q(k0 + 192)
;     __syncthreads();
;     MMA_TILE(1)
;     ST_LDS(0, pa0, pa1, pa2, pa3, pb0, pb1, pb2, pb3)
;     GL_P(k0 + 256)
;     __syncthreads();
;   }
;   MMA_TILE(0)
;   ST_LDS(1, qa0, qa1, qa2, qa3, qb0, qb1, qb2, qb3)
;   GL_Q(K - 64)
;   __syncthreads();
;   MMA_TILE(1)
;   ST_LDS(0, pa0, pa1, pa2, pa3, pb0, pb1, pb2, pb3)
;   __syncthreads();
	s_setprio 1
	v_mfma_f32_32x32x16_bf16 v[16:31], v[168:171], v[172:175], v[16:31]
	v_mfma_f32_32x32x16_bf16 v[0:15], v[168:171], v[184:187], v[0:15]
	v_mfma_f32_32x32x16_bf16 v[48:63], v[176:179], v[180:183], v[48:63]
	v_mfma_f32_32x32x16_bf16 v[32:47], v[176:179], v[188:191], v[32:47]
	v_mfma_f32_32x32x16_bf16 v[16:31], v[192:195], v[180:183], v[16:31]
	v_mfma_f32_32x32x16_bf16 v[0:15], v[192:195], v[188:191], v[0:15]
	s_cbranch_scc1 .LBB0_208
	ds_read_b128 v[148:151], v128
	ds_read_b128 v[168:171], v129 offset:18432
	ds_read_b128 v[172:175], v129 offset:23040
	s_mov_b64 s[52:53], -1
	s_cmp_gt_i32 s60, 15
	s_waitcnt lgkmcnt(1)
	v_mfma_f32_32x32x16_bf16 v[48:63], v[148:151], v[168:171], v[48:63]
	s_waitcnt lgkmcnt(0)
	v_mfma_f32_32x32x16_bf16 v[32:47], v[148:151], v[172:175], v[32:47]
	ds_read_b128 v[148:151], v128 offset:4608
	s_waitcnt lgkmcnt(0)
	v_mfma_f32_32x32x16_bf16 v[16:31], v[148:151], v[168:171], v[16:31]
	v_mfma_f32_32x32x16_bf16 v[0:15], v[148:151], v[172:175], v[0:15]
	ds_read_b128 v[148:151], v128 offset:32
	ds_read_b128 v[168:171], v129 offset:18464
	ds_read_b128 v[172:175], v129 offset:23072
	s_waitcnt lgkmcnt(1)
	v_mfma_f32_32x32x16_bf16 v[48:63], v[148:151], v[168:171], v[48:63]
	s_waitcnt lgkmcnt(0)
	v_mfma_f32_32x32x16_bf16 v[32:47], v[148:151], v[172:175], v[32:47]
	ds_read_b128 v[148:151], v128 offset:4640
	s_waitcnt lgkmcnt(0)
	v_mfma_f32_32x32x16_bf16 v[16:31], v[148:151], v[168:171], v[16:31]
	v_mfma_f32_32x32x16_bf16 v[0:15], v[148:151], v[172:175], v[0:15]
	ds_read_b128 v[148:151], v128 offset:64
	ds_read_b128 v[168:171], v129 offset:18496
	ds_read_b128 v[172:175], v129 offset:23104
	s_waitcnt lgkmcnt(1)
	v_mfma_f32_32x32x16_bf16 v[48:63], v[148:151], v[168:171], v[48:63]
	s_waitcnt lgkmcnt(0)
	v_mfma_f32_32x32x16_bf16 v[32:47], v[148:151], v[172:175], v[32:47]
	ds_read_b128 v[148:151], v128 offset:4672
	s_waitcnt lgkmcnt(0)
	v_mfma_f32_32x32x16_bf16 v[16:31], v[148:151], v[168:171], v[16:31]
	v_mfma_f32_32x32x16_bf16 v[0:15], v[148:151], v[172:175], v[0:15]
	ds_read_b128 v[148:151], v128 offset:96
	ds_read_b128 v[168:171], v129 offset:18528
	ds_read_b128 v[172:175], v129 offset:23136
	s_waitcnt lgkmcnt(1)
	v_mfma_f32_32x32x16_bf16 v[48:63], v[148:151], v[168:171], v[48:63]
	s_waitcnt lgkmcnt(0)
	v_mfma_f32_32x32x16_bf16 v[32:47], v[148:151], v[172:175], v[32:47]
	ds_read_b128 v[148:151], v128 offset:4704
	s_setprio 0
	s_waitcnt vmcnt(15)
	ds_write_b128 v130, v[96:99] offset:36864
	s_waitcnt vmcnt(14)
	ds_write_b128 v130, v[100:103] offset:41472
	s_waitcnt vmcnt(13)
	ds_write_b128 v130, v[104:107] offset:46080
	s_waitcnt vmcnt(12)
	ds_write_b128 v130, v[108:111] offset:50688
	s_waitcnt vmcnt(11)
	ds_write_b128 v130, v[112:115] offset:55296
	s_waitcnt vmcnt(10)
	ds_write_b128 v130, v[116:119] offset:59904
	s_waitcnt vmcnt(9)
	ds_write_b128 v130, v[120:123] offset:64512
	s_waitcnt vmcnt(8)
	ds_write_b128 v131, v[124:127] offset:13824
	global_load_dwordx4 v[96:99], v[142:143], off offset:3968
	global_load_dwordx4 v[100:103], v[138:139], off offset:3968
	global_load_dwordx4 v[104:107], v[144:145], off offset:3968
	global_load_dwordx4 v[108:111], v[146:147], off offset:3968
	global_load_dwordx4 v[112:115], v[132:133], off offset:3968
	global_load_dwordx4 v[116:119], v[134:135], off offset:3968
	global_load_dwordx4 v[120:123], v[136:137], off offset:3968
	global_load_dwordx4 v[124:127], v[140:141], off offset:3968
	s_waitcnt lgkmcnt(0)
	s_barrier
	s_setprio 1
	ds_read_b128 v[132:135], v128 offset:36864
	ds_read_b128 v[136:139], v129 offset:55296
	ds_read_b128 v[140:143], v129 offset:59904
	s_waitcnt lgkmcnt(1)
	v_mfma_f32_32x32x16_bf16 v[48:63], v[132:135], v[136:139], v[48:63]
	s_waitcnt lgkmcnt(0)
	v_mfma_f32_32x32x16_bf16 v[32:47], v[132:135], v[140:143], v[32:47]
	ds_read_b128 v[132:135], v128 offset:41472
	v_mfma_f32_32x32x16_bf16 v[16:31], v[148:151], v[168:171], v[16:31]
	v_mfma_f32_32x32x16_bf16 v[0:15], v[148:151], v[172:175], v[0:15]
	s_waitcnt lgkmcnt(0)
	v_mfma_f32_32x32x16_bf16 v[16:31], v[132:135], v[136:139], v[16:31]
	v_mfma_f32_32x32x16_bf16 v[0:15], v[132:135], v[140:143], v[0:15]
	ds_read_b128 v[132:135], v128 offset:36896
	ds_read_b128 v[136:139], v129 offset:55328
	ds_read_b128 v[140:143], v129 offset:59936
	s_waitcnt lgkmcnt(1)
	v_mfma_f32_32x32x16_bf16 v[48:63], v[132:135], v[136:139], v[48:63]
	s_waitcnt lgkmcnt(0)
	v_mfma_f32_32x32x16_bf16 v[32:47], v[132:135], v[140:143], v[32:47]
	ds_read_b128 v[132:135], v128 offset:41504
	s_waitcnt lgkmcnt(0)
	v_mfma_f32_32x32x16_bf16 v[16:31], v[132:135], v[136:139], v[16:31]
	v_mfma_f32_32x32x16_bf16 v[0:15], v[132:135], v[140:143], v[0:15]
	ds_read_b128 v[132:135], v128 offset:36928
	ds_read_b128 v[136:139], v129 offset:55360
	ds_read_b128 v[140:143], v129 offset:59968
	s_waitcnt lgkmcnt(1)
	v_mfma_f32_32x32x16_bf16 v[48:63], v[132:135], v[136:139], v[48:63]
	s_waitcnt lgkmcnt(0)
	v_mfma_f32_32x32x16_bf16 v[32:47], v[132:135], v[140:143], v[32:47]
	ds_read_b128 v[132:135], v128 offset:41536
	s_waitcnt lgkmcnt(0)
	v_mfma_f32_32x32x16_bf16 v[16:31], v[132:135], v[136:139], v[16:31]
	v_mfma_f32_32x32x16_bf16 v[0:15], v[132:135], v[140:143], v[0:15]
	ds_read_b128 v[132:135], v128 offset:36960
	ds_read_b128 v[136:139], v129 offset:55392
	ds_read_b128 v[140:143], v129 offset:60000
	s_waitcnt lgkmcnt(1)
	v_mfma_f32_32x32x16_bf16 v[48:63], v[132:135], v[136:139], v[48:63]
	s_waitcnt lgkmcnt(0)
	v_mfma_f32_32x32x16_bf16 v[32:47], v[132:135], v[140:143], v[32:47]
	ds_read_b128 v[132:135], v128 offset:41568
	s_setprio 0
	s_waitcnt vmcnt(15)
	ds_write_b128 v130, v[92:95]
	s_waitcnt vmcnt(14)
	ds_write_b128 v130, v[64:67] offset:4608
	s_waitcnt vmcnt(13)
	ds_write_b128 v130, v[68:71] offset:9216
	s_waitcnt vmcnt(12)
	ds_write_b128 v130, v[84:87] offset:13824
	s_waitcnt vmcnt(11)
	ds_write_b128 v130, v[72:75] offset:18432
	s_waitcnt vmcnt(10)
	ds_write_b128 v130, v[76:79] offset:23040
	s_waitcnt vmcnt(9)
	ds_write_b128 v130, v[80:83] offset:27648
	s_waitcnt vmcnt(8)
	ds_write_b128 v130, v[88:91] offset:32256
	s_waitcnt lgkmcnt(0)
	s_barrier
; DI void gemm_128_deep(const bf16_t* __restrict__ A, int lda, const bf16_t* __restrict__ B, int ldb, int K, f32x16 (&acc)[2][2], bf16_t* sA, bf16_t* sBunused) {
;     ...
;   MMA_TILE(1)
;   ST_LDS(0, pa0, pa1, pa2, pa3, pb0, pb1, pb2, pb3)
;   __syncthreads();
;   MMA_TILE(0)
;   ST_LDS(1, qa0, qa1, qa2, qa3, qb0, qb1, qb2, qb3)
;   __syncthreads();
;   MMA_TILE(1)
;   __syncthreads();
	s_setprio 1
	ds_read_b128 v[64:67], v128
	ds_read_b128 v[68:71], v129 offset:18432
	ds_read_b128 v[72:75], v129 offset:23040
	s_waitcnt lgkmcnt(1)
	v_mfma_f32_32x32x16_bf16 v[48:63], v[64:67], v[68:71], v[48:63]
	s_waitcnt lgkmcnt(0)
	v_mfma_f32_32x32x16_bf16 v[32:47], v[64:67], v[72:75], v[32:47]
	ds_read_b128 v[64:67], v128 offset:4608
	v_mfma_f32_32x32x16_bf16 v[16:31], v[132:135], v[136:139], v[16:31]
	v_mfma_f32_32x32x16_bf16 v[0:15], v[132:135], v[140:143], v[0:15]
	s_waitcnt lgkmcnt(0)
	v_mfma_f32_32x32x16_bf16 v[16:31], v[64:67], v[68:71], v[16:31]
	v_mfma_f32_32x32x16_bf16 v[0:15], v[64:67], v[72:75], v[0:15]
	ds_read_b128 v[64:67], v128 offset:32
	ds_read_b128 v[68:71], v129 offset:18464
	ds_read_b128 v[72:75], v129 offset:23072
	s_waitcnt lgkmcnt(1)
	v_mfma_f32_32x32x16_bf16 v[48:63], v[64:67], v[68:71], v[48:63]
	s_waitcnt lgkmcnt(0)
	v_mfma_f32_32x32x16_bf16 v[32:47], v[64:67], v[72:75], v[32:47]
	ds_read_b128 v[64:67], v128 offset:4640
	s_waitcnt lgkmcnt(0)
	v_mfma_f32_32x32x16_bf16 v[16:31], v[64:67], v[68:71], v[16:31]
	v_mfma_f32_32x32x16_bf16 v[0:15], v[64:67], v[72:75], v[0:15]
	ds_read_b128 v[64:67], v128 offset:64
	ds_read_b128 v[68:71], v129 offset:18496
	ds_read_b128 v[72:75], v129 offset:23104
	s_waitcnt lgkmcnt(1)
	v_mfma_f32_32x32x16_bf16 v[48:63], v[64:67], v[68:71], v[48:63]
	s_waitcnt lgkmcnt(0)
	v_mfma_f32_32x32x16_bf16 v[32:47], v[64:67], v[72:75], v[32:47]
	ds_read_b128 v[64:67], v128 offset:4672
	s_waitcnt lgkmcnt(0)
	v_mfma_f32_32x32x16_bf16 v[16:31], v[64:67], v[68:71], v[16:31]
	v_mfma_f32_32x32x16_bf16 v[0:15], v[64:67], v[72:75], v[0:15]
	ds_read_b128 v[64:67], v128 offset:96
	ds_read_b128 v[68:71], v129 offset:18528
	ds_read_b128 v[72:75], v129 offset:23136
	s_waitcnt lgkmcnt(1)
	v_mfma_f32_32x32x16_bf16 v[48:63], v[64:67], v[68:71], v[48:63]
	s_waitcnt lgkmcnt(0)
	v_mfma_f32_32x32x16_bf16 v[32:47], v[64:67], v[72:75], v[32:47]
	ds_read_b128 v[64:67], v128 offset:4704
	s_setprio 0
	s_waitcnt vmcnt(7)
	ds_write_b128 v130, v[96:99] offset:36864
	s_waitcnt vmcnt(6)
	ds_write_b128 v130, v[100:103] offset:41472
	s_waitcnt vmcnt(5)
	ds_write_b128 v130, v[104:107] offset:46080
	s_waitcnt vmcnt(4)
	ds_write_b128 v130, v[108:111] offset:50688
	s_waitcnt vmcnt(3)
	ds_write_b128 v130, v[112:115] offset:55296
	s_waitcnt vmcnt(2)
	ds_write_b128 v130, v[116:119] offset:59904
	s_waitcnt vmcnt(1)
	ds_write_b128 v130, v[120:123] offset:64512
	s_waitcnt vmcnt(0)
	ds_write_b128 v131, v[124:127] offset:13824
	s_waitcnt lgkmcnt(0)
	s_barrier
	s_setprio 1
	v_mfma_f32_32x32x16_bf16 v[16:31], v[64:67], v[68:71], v[16:31]
	v_mfma_f32_32x32x16_bf16 v[0:15], v[64:67], v[72:75], v[0:15]
	ds_read_b128 v[64:67], v128 offset:36864
	ds_read_b128 v[68:71], v129 offset:55296
	ds_read_b128 v[72:75], v129 offset:59904
	s_waitcnt lgkmcnt(1)
	v_mfma_f32_32x32x16_bf16 v[48:63], v[64:67], v[68:71], v[48:63]
	s_waitcnt lgkmcnt(0)
	v_mfma_f32_32x32x16_bf16 v[32:47], v[64:67], v[72:75], v[32:47]
	ds_read_b128 v[64:67], v128 offset:41472
	s_waitcnt lgkmcnt(0)
	v_mfma_f32_32x32x16_bf16 v[16:31], v[64:67], v[68:71], v[16:31]
	v_mfma_f32_32x32x16_bf16 v[0:15], v[64:67], v[72:75], v[0:15]
	ds_read_b128 v[64:67], v128 offset:36896
	ds_read_b128 v[68:71], v129 offset:55328
	ds_read_b128 v[72:75], v129 offset:59936
	s_waitcnt lgkmcnt(1)
	v_mfma_f32_32x32x16_bf16 v[48:63], v[64:67], v[68:71], v[48:63]
	s_waitcnt lgkmcnt(0)
	v_mfma_f32_32x32x16_bf16 v[32:47], v[64:67], v[72:75], v[32:47]
	ds_read_b128 v[64:67], v128 offset:41504
	s_waitcnt lgkmcnt(0)
	v_mfma_f32_32x32x16_bf16 v[16:31], v[64:67], v[68:71], v[16:31]
	v_mfma_f32_32x32x16_bf16 v[0:15], v[64:67], v[72:75], v[0:15]
	ds_read_b128 v[64:67], v128 offset:36928
	ds_read_b128 v[68:71], v129 offset:55360
	ds_read_b128 v[72:75], v129 offset:59968
	s_waitcnt lgkmcnt(1)
	v_mfma_f32_32x32x16_bf16 v[48:63], v[64:67], v[68:71], v[48:63]
	s_waitcnt lgkmcnt(0)
	v_mfma_f32_32x32x16_bf16 v[32:47], v[64:67], v[72:75], v[32:47]
	ds_read_b128 v[64:67], v128 offset:41536
	s_waitcnt lgkmcnt(0)
	v_mfma_f32_32x32x16_bf16 v[16:31], v[64:67], v[68:71], v[16:31]
	v_mfma_f32_32x32x16_bf16 v[0:15], v[64:67], v[72:75], v[0:15]
	ds_read_b128 v[64:67], v128 offset:36960
	ds_read_b128 v[68:71], v129 offset:55392
	ds_read_b128 v[72:75], v129 offset:60000
	s_waitcnt lgkmcnt(1)
	v_mfma_f32_32x32x16_bf16 v[48:63], v[64:67], v[68:71], v[48:63]
	s_waitcnt lgkmcnt(0)
	v_mfma_f32_32x32x16_bf16 v[32:47], v[64:67], v[72:75], v[32:47]
	ds_read_b128 v[64:67], v128 offset:41568
	s_waitcnt lgkmcnt(0)
	s_barrier
	s_setprio 1
	v_mfma_f32_32x32x16_bf16 v[16:31], v[64:67], v[68:71], v[16:31]
	v_mfma_f32_32x32x16_bf16 v[0:15], v[64:67], v[72:75], v[0:15]
	s_setprio 0
	s_cbranch_scc1 .LBB0_213
	s_andn2_b64 vcc, exec, s[52:53]
	s_cbranch_vccz .LBB0_225

; DI void gemm_128_deep(const bf16_t* __restrict__ A, int lda, const bf16_t* __restrict__ B, int ldb, int K, f32x16 (&acc)[2][2], bf16_t* sA, bf16_t* sBunused) {
;     ...
;   for (int k0 = 0; k0 < K - 256; k0 += 128) {
;     MMA_TILE(0)
;     ST_LDS(1, qa0, qa1, qa2, qa3, qb0, qb1, qb2, qb3)
;     GL_Q(k0 + 192)
;     __syncthreads();
;     MMA_TILE(1)
;     ST_LDS(0, pa0, pa1, pa2, pa3, pb0, pb1, pb2, pb3)
;     GL_P(k0 + 256)
;     __syncthreads();
;   }
.LBB0_954:
	ds_read_b128 v[152:155], v128
	ds_read_b128 v[168:171], v129 offset:18432
	ds_read_b128 v[172:175], v129 offset:23040
	s_mov_b32 s4, 0x1ba64000
	s_mov_b32 s38, 0x1a064000
	s_mov_b32 s6, 0x1baa4000
	s_waitcnt lgkmcnt(1)
	v_mfma_f32_32x32x16_bf16 v[48:63], v[152:155], v[168:171], v[48:63]
	s_mov_b32 s10, 0x1bac4000
	s_mov_b32 s40, 0x1a084000
	s_mov_b32 s42, 0x1a0a4000
	s_mov_b32 s44, 0x1a0c4000
	s_addk_i32 s47, 0x80
	s_cmpk_lt_u32 s47, 0x680
	s_waitcnt lgkmcnt(0)
	v_mfma_f32_32x32x16_bf16 v[32:47], v[152:155], v[172:175], v[32:47]
	ds_read_b128 v[152:155], v128 offset:4608
	s_waitcnt lgkmcnt(0)
	v_mfma_f32_32x32x16_bf16 v[16:31], v[152:155], v[168:171], v[16:31]
	v_mfma_f32_32x32x16_bf16 v[0:15], v[152:155], v[172:175], v[0:15]
	ds_read_b128 v[152:155], v128 offset:32
	ds_read_b128 v[168:171], v129 offset:18464
	ds_read_b128 v[172:175], v129 offset:23072
	s_waitcnt lgkmcnt(1)
	v_mfma_f32_32x32x16_bf16 v[48:63], v[152:155], v[168:171], v[48:63]
	s_waitcnt lgkmcnt(0)
	v_mfma_f32_32x32x16_bf16 v[32:47], v[152:155], v[172:175], v[32:47]
	ds_read_b128 v[152:155], v128 offset:4640
	s_waitcnt lgkmcnt(0)
	v_mfma_f32_32x32x16_bf16 v[16:31], v[152:155], v[168:171], v[16:31]
	ds_read_b128 v[168:171], v128 offset:64
	v_mfma_f32_32x32x16_bf16 v[0:15], v[152:155], v[172:175], v[0:15]
	ds_read_b128 v[176:179], v128 offset:4672
	ds_read_b128 v[172:175], v129 offset:18496
	ds_read_b128 v[194:197], v129 offset:23104
	ds_read_b128 v[198:201], v128 offset:96
	ds_read_b128 v[202:205], v128 offset:4704
	ds_read_b128 v[206:209], v129 offset:18528
	ds_read_b128 v[210:213], v129 offset:23136
	s_waitcnt lgkmcnt(5)
	v_mfma_f32_32x32x16_bf16 v[48:63], v[168:171], v[172:175], v[48:63]
	s_waitcnt lgkmcnt(4)
	v_mfma_f32_32x32x16_bf16 v[32:47], v[168:171], v[194:197], v[32:47]
	v_mfma_f32_32x32x16_bf16 v[16:31], v[176:179], v[172:175], v[16:31]
	v_mfma_f32_32x32x16_bf16 v[0:15], v[176:179], v[194:197], v[0:15]
	s_waitcnt lgkmcnt(1)
	v_mfma_f32_32x32x16_bf16 v[48:63], v[198:201], v[206:209], v[48:63]
	s_setprio 0
	s_waitcnt vmcnt(15)
	ds_write_b128 v130, v[108:111] offset:36864
	s_waitcnt vmcnt(14)
	ds_write_b128 v130, v[96:99] offset:41472
	s_waitcnt vmcnt(13)
	ds_write_b128 v130, v[100:103] offset:46080
	s_waitcnt vmcnt(12)
	ds_write_b128 v130, v[104:107] offset:50688
	s_waitcnt vmcnt(11)
	ds_write_b128 v130, v[112:115] offset:55296
	s_waitcnt vmcnt(10)
	ds_write_b128 v130, v[116:119] offset:59904
	s_waitcnt vmcnt(9)
	ds_write_b128 v130, v[120:123] offset:64512
	v_lshl_add_u64 v[96:97], v[150:151], 0, v[156:157]
	v_lshl_add_u64 v[98:99], v[148:149], 0, v[156:157]
	v_add_co_u32_e32 v152, vcc, s4, v96
	s_mov_b32 s4, 0x1ba84000
	s_waitcnt vmcnt(8)
	ds_write_b128 v131, v[124:127] offset:13824
	v_add_co_u32_e64 v154, s[4:5], s4, v96
	s_nop 1
	v_addc_co_u32_e32 v153, vcc, 0, v97, vcc
	s_nop 0
	s_nop 0
	v_addc_co_u32_e64 v155, vcc, 0, v97, s[4:5]
	v_add_co_u32_e64 v168, s[6:7], s6, v96
	v_add_co_u32_e64 v170, s[10:11], s10, v96
	s_nop 0
	s_nop 0
	v_addc_co_u32_e64 v169, vcc, 0, v97, s[6:7]
	s_nop 1
	v_addc_co_u32_e64 v171, vcc, 0, v97, s[10:11]
	v_add_co_u32_e64 v172, s[38:39], s38, v98
	v_add_co_u32_e64 v174, s[40:41], s40, v98
	s_nop 0
	s_nop 0
	v_addc_co_u32_e64 v173, vcc, 0, v99, s[38:39]
	s_nop 1
	v_addc_co_u32_e64 v175, vcc, 0, v99, s[40:41]
	v_add_co_u32_e64 v176, s[42:43], s42, v98
	v_add_co_u32_e64 v178, s[44:45], s44, v98
	s_nop 0
	s_nop 0
	v_addc_co_u32_e64 v177, vcc, 0, v99, s[42:43]
	s_nop 1
	v_addc_co_u32_e64 v179, vcc, 0, v99, s[44:45]
	global_load_dwordx4 v[108:111], v[152:153], off offset:2176
	global_load_dwordx4 v[96:99], v[154:155], off offset:2176
	global_load_dwordx4 v[100:103], v[168:169], off offset:2176
	global_load_dwordx4 v[104:107], v[170:171], off offset:2176
	global_load_dwordx4 v[112:115], v[172:173], off offset:2176
	global_load_dwordx4 v[116:119], v[174:175], off offset:2176
	global_load_dwordx4 v[120:123], v[176:177], off offset:2176
	global_load_dwordx4 v[124:127], v[178:179], off offset:2176
	s_waitcnt lgkmcnt(0)
	s_barrier
	s_setprio 1
	v_lshl_add_u64 v[148:149], v[148:149], 0, s[94:95]
	v_lshl_add_u64 v[150:151], v[150:151], 0, s[94:95]
	v_mfma_f32_32x32x16_bf16 v[32:47], v[198:201], v[210:213], v[32:47]
	ds_read_b128 v[194:197], v128 offset:36864
	ds_read_b128 v[198:201], v129 offset:55296
	v_mfma_f32_32x32x16_bf16 v[16:31], v[202:205], v[206:209], v[16:31]
	v_mfma_f32_32x32x16_bf16 v[0:15], v[202:205], v[210:213], v[0:15]
	ds_read_b128 v[202:205], v129 offset:59904
	s_waitcnt lgkmcnt(1)
	v_mfma_f32_32x32x16_bf16 v[48:63], v[194:197], v[198:201], v[48:63]
	s_waitcnt lgkmcnt(0)
	v_mfma_f32_32x32x16_bf16 v[32:47], v[194:197], v[202:205], v[32:47]
	ds_read_b128 v[194:197], v128 offset:41472
	s_waitcnt lgkmcnt(0)
	v_mfma_f32_32x32x16_bf16 v[16:31], v[194:197], v[198:201], v[16:31]
	v_mfma_f32_32x32x16_bf16 v[0:15], v[194:197], v[202:205], v[0:15]
	ds_read_b128 v[194:197], v128 offset:36896
	ds_read_b128 v[198:201], v129 offset:55328
	ds_read_b128 v[202:205], v129 offset:59936
	s_waitcnt lgkmcnt(1)
	v_mfma_f32_32x32x16_bf16 v[48:63], v[194:197], v[198:201], v[48:63]
	s_waitcnt lgkmcnt(0)
	v_mfma_f32_32x32x16_bf16 v[32:47], v[194:197], v[202:205], v[32:47]
	ds_read_b128 v[194:197], v128 offset:41504
	s_waitcnt lgkmcnt(0)
	v_mfma_f32_32x32x16_bf16 v[16:31], v[194:197], v[198:201], v[16:31]
	v_mfma_f32_32x32x16_bf16 v[0:15], v[194:197], v[202:205], v[0:15]
	ds_read_b128 v[194:197], v128 offset:36928
	ds_read_b128 v[198:201], v129 offset:55360
	ds_read_b128 v[202:205], v129 offset:59968
	s_waitcnt lgkmcnt(1)
	v_mfma_f32_32x32x16_bf16 v[48:63], v[194:197], v[198:201], v[48:63]
	s_waitcnt lgkmcnt(0)
	v_mfma_f32_32x32x16_bf16 v[32:47], v[194:197], v[202:205], v[32:47]
	ds_read_b128 v[194:197], v128 offset:41536
	s_waitcnt lgkmcnt(0)
	v_mfma_f32_32x32x16_bf16 v[16:31], v[194:197], v[198:201], v[16:31]
	v_mfma_f32_32x32x16_bf16 v[0:15], v[194:197], v[202:205], v[0:15]
	ds_read_b128 v[194:197], v128 offset:36960
	ds_read_b128 v[198:201], v129 offset:55392
	ds_read_b128 v[202:205], v128 offset:41568
	ds_read_b128 v[206:209], v129 offset:60000
	s_setprio 0
	s_waitcnt vmcnt(13)
	ds_write_b128 v130, v[92:95]
	ds_write_b128 v130, v[64:67] offset:4608
	ds_write_b128 v130, v[68:71] offset:9216
	s_waitcnt vmcnt(11)
	ds_write_b128 v130, v[84:87] offset:13824
	ds_write_b128 v130, v[72:75] offset:18432
	s_waitcnt vmcnt(10)
	ds_write_b128 v130, v[76:79] offset:23040
	s_waitcnt vmcnt(9)
	ds_write_b128 v130, v[80:83] offset:27648
	s_waitcnt vmcnt(8)
	ds_write_b128 v130, v[88:91] offset:32256
	global_load_dwordx4 v[92:95], v[152:153], off offset:2304
	global_load_dwordx4 v[64:67], v[154:155], off offset:2304
	global_load_dwordx4 v[68:71], v[168:169], off offset:2304
	global_load_dwordx4 v[84:87], v[170:171], off offset:2304
	global_load_dwordx4 v[72:75], v[172:173], off offset:2304
	global_load_dwordx4 v[76:79], v[174:175], off offset:2304
	global_load_dwordx4 v[80:83], v[176:177], off offset:2304
	global_load_dwordx4 v[88:91], v[178:179], off offset:2304
	s_waitcnt lgkmcnt(0)
	s_barrier
; DI void gemm_128_deep(const bf16_t* __restrict__ A, int lda, const bf16_t* __restrict__ B, int ldb, int K, f32x16 (&acc)[2][2], bf16_t* sA, bf16_t* sBunused) {
;     ...
;   for (int k0 = 0; k0 < K - 256; k0 += 128) {
;     MMA_TILE(0)
;     ST_LDS(1, qa0, qa1, qa2, qa3, qb0, qb1, qb2, qb3)
;     GL_Q(k0 + 192)
;     __syncthreads();
;     MMA_TILE(1)
;     ST_LDS(0, pa0, pa1, pa2, pa3, pb0, pb1, pb2, pb3)
;     GL_P(k0 + 256)
;     __syncthreads();
;   }
;   MMA_TILE(0)
;   ST_LDS(1, qa0, qa1, qa2, qa3, qb0, qb1, qb2, qb3)
;   GL_Q(K - 64)
;   __syncthreads();
;   MMA_TILE(1)
;   ST_LDS(0, pa0, pa1, pa2, pa3, pb0, pb1, pb2, pb3)
;   __syncthreads();
; DI void phase_out(CP p, const Ptrs& w, int l, bf16_t* sA, bf16_t* sB) {
;     ...
;     int b = m0 / TPB, ib = m0 - b * TPB;
;     bool isctx = ib < CTXL;
;     f32x16 acc[2][2];
;     zero_acc(acc);
;     gemm_128_deep(w.R2 + (size_t)m0 * 2048, 2048, out_t + (size_t)n0 * 2048, 2048, 2048, acc, sA, sB);
;     const float* gate = w.mod + (l * 3 + (isctx ? 2 : b)) * 6144 + 4096;
	s_setprio 1
	v_mfma_f32_32x32x16_bf16 v[48:63], v[194:197], v[198:201], v[48:63]
	v_mfma_f32_32x32x16_bf16 v[32:47], v[194:197], v[206:209], v[32:47]
	v_mfma_f32_32x32x16_bf16 v[16:31], v[202:205], v[198:201], v[16:31]
	v_mfma_f32_32x32x16_bf16 v[0:15], v[202:205], v[206:209], v[0:15]
	s_cbranch_scc1 .LBB0_954
	ds_read_b128 v[148:151], v128
	ds_read_b128 v[152:155], v129 offset:18432
	ds_read_b128 v[168:171], v129 offset:23040
	s_mul_hi_i32 s4, s90, 0x3e0f83e1
	s_lshr_b32 s5, s4, 31
	s_ashr_i32 s39, s4, 4
	s_waitcnt lgkmcnt(1)
	v_mfma_f32_32x32x16_bf16 v[48:63], v[148:151], v[152:155], v[48:63]
	s_add_i32 s39, s39, s5
	s_mul_i32 s38, s39, 0x2100
	s_sub_i32 s10, s48, s38
	s_cmpk_lt_i32 s10, 0x100
	s_cselect_b64 s[4:5], -1, 0
	s_and_b64 s[6:7], s[4:5], exec
	s_cselect_b32 s6, 2, s39
	s_waitcnt lgkmcnt(0)
	v_mfma_f32_32x32x16_bf16 v[32:47], v[148:151], v[168:171], v[32:47]
	ds_read_b128 v[148:151], v128 offset:4608
	v_readlane_b32 s7, v254, 56
	s_add_i32 s6, s6, s7
	s_mulk_i32 s6, 0x1800
	s_ashr_i32 s7, s6, 31
	s_lshl_b64 s[6:7], s[6:7], 2
	s_add_u32 s6, s78, s6
	s_waitcnt lgkmcnt(0)
	v_mfma_f32_32x32x16_bf16 v[16:31], v[148:151], v[152:155], v[16:31]
	s_addc_u32 s7, s79, s7
	s_add_u32 s6, s6, 0x4000
	s_addc_u32 s7, s7, 0
	v_readlane_b32 s40, v254, 54
	v_readlane_b32 s41, v254, 55
	s_and_b64 vcc, exec, s[40:41]
	v_mfma_f32_32x32x16_bf16 v[0:15], v[148:151], v[168:171], v[0:15]
	ds_read_b128 v[148:151], v128 offset:32
	ds_read_b128 v[152:155], v129 offset:18464
	ds_read_b128 v[168:171], v129 offset:23072
	s_waitcnt lgkmcnt(1)
	v_mfma_f32_32x32x16_bf16 v[48:63], v[148:151], v[152:155], v[48:63]
	s_waitcnt lgkmcnt(0)
	v_mfma_f32_32x32x16_bf16 v[32:47], v[148:151], v[168:171], v[32:47]
	ds_read_b128 v[148:151], v128 offset:4640
	s_waitcnt lgkmcnt(0)
	v_mfma_f32_32x32x16_bf16 v[16:31], v[148:151], v[152:155], v[16:31]
	v_mfma_f32_32x32x16_bf16 v[0:15], v[148:151], v[168:171], v[0:15]
	ds_read_b128 v[148:151], v128 offset:64
	ds_read_b128 v[152:155], v129 offset:18496
	ds_read_b128 v[168:171], v129 offset:23104
	s_waitcnt lgkmcnt(1)
	v_mfma_f32_32x32x16_bf16 v[48:63], v[148:151], v[152:155], v[48:63]
	s_waitcnt lgkmcnt(0)
	v_mfma_f32_32x32x16_bf16 v[32:47], v[148:151], v[168:171], v[32:47]
	ds_read_b128 v[148:151], v128 offset:4672
	s_waitcnt lgkmcnt(0)
	v_mfma_f32_32x32x16_bf16 v[16:31], v[148:151], v[152:155], v[16:31]
	v_mfma_f32_32x32x16_bf16 v[0:15], v[148:151], v[168:171], v[0:15]
	ds_read_b128 v[148:151], v128 offset:96
	ds_read_b128 v[152:155], v129 offset:18528
	ds_read_b128 v[168:171], v129 offset:23136
	s_waitcnt lgkmcnt(1)
	v_mfma_f32_32x32x16_bf16 v[48:63], v[148:151], v[152:155], v[48:63]
	s_waitcnt lgkmcnt(0)
	v_mfma_f32_32x32x16_bf16 v[32:47], v[148:151], v[168:171], v[32:47]
	ds_read_b128 v[148:151], v128 offset:4704
	s_setprio 0
	s_waitcnt vmcnt(15)
	ds_write_b128 v130, v[108:111] offset:36864
	s_waitcnt vmcnt(14)
	ds_write_b128 v130, v[96:99] offset:41472
	s_waitcnt vmcnt(13)
	ds_write_b128 v130, v[100:103] offset:46080
	s_waitcnt vmcnt(12)
	ds_write_b128 v130, v[104:107] offset:50688
	s_waitcnt vmcnt(11)
	ds_write_b128 v130, v[112:115] offset:55296
	s_waitcnt vmcnt(10)
	ds_write_b128 v130, v[116:119] offset:59904
	s_waitcnt vmcnt(9)
	ds_write_b128 v130, v[120:123] offset:64512
	s_waitcnt vmcnt(8)
	ds_write_b128 v131, v[124:127] offset:13824
	global_load_dwordx4 v[96:99], v[142:143], off offset:3968
	global_load_dwordx4 v[100:103], v[138:139], off offset:3968
	global_load_dwordx4 v[104:107], v[144:145], off offset:3968
	global_load_dwordx4 v[108:111], v[146:147], off offset:3968
	global_load_dwordx4 v[112:115], v[132:133], off offset:3968
	global_load_dwordx4 v[116:119], v[134:135], off offset:3968
	global_load_dwordx4 v[120:123], v[136:137], off offset:3968
	global_load_dwordx4 v[124:127], v[140:141], off offset:3968
	s_waitcnt lgkmcnt(0)
	s_barrier
	s_setprio 1
	ds_read_b128 v[132:135], v128 offset:36864
	ds_read_b128 v[136:139], v129 offset:55296
	ds_read_b128 v[140:143], v129 offset:59904
	s_waitcnt lgkmcnt(1)
	v_mfma_f32_32x32x16_bf16 v[48:63], v[132:135], v[136:139], v[48:63]
	s_waitcnt lgkmcnt(0)
	v_mfma_f32_32x32x16_bf16 v[32:47], v[132:135], v[140:143], v[32:47]
	ds_read_b128 v[132:135], v128 offset:41472
	v_mfma_f32_32x32x16_bf16 v[16:31], v[148:151], v[152:155], v[16:31]
	v_mfma_f32_32x32x16_bf16 v[0:15], v[148:151], v[168:171], v[0:15]
	s_waitcnt lgkmcnt(0)
	v_mfma_f32_32x32x16_bf16 v[16:31], v[132:135], v[136:139], v[16:31]
	v_mfma_f32_32x32x16_bf16 v[0:15], v[132:135], v[140:143], v[0:15]
	ds_read_b128 v[132:135], v128 offset:36896
	ds_read_b128 v[136:139], v129 offset:55328
	ds_read_b128 v[140:143], v129 offset:59936
	s_waitcnt lgkmcnt(1)
	v_mfma_f32_32x32x16_bf16 v[48:63], v[132:135], v[136:139], v[48:63]
	s_waitcnt lgkmcnt(0)
	v_mfma_f32_32x32x16_bf16 v[32:47], v[132:135], v[140:143], v[32:47]
	ds_read_b128 v[132:135], v128 offset:41504
	s_waitcnt lgkmcnt(0)
	v_mfma_f32_32x32x16_bf16 v[16:31], v[132:135], v[136:139], v[16:31]
	v_mfma_f32_32x32x16_bf16 v[0:15], v[132:135], v[140:143], v[0:15]
	ds_read_b128 v[132:135], v128 offset:36928
	ds_read_b128 v[136:139], v129 offset:55360
	ds_read_b128 v[140:143], v129 offset:59968
	s_waitcnt lgkmcnt(1)
	v_mfma_f32_32x32x16_bf16 v[48:63], v[132:135], v[136:139], v[48:63]
	s_waitcnt lgkmcnt(0)
	v_mfma_f32_32x32x16_bf16 v[32:47], v[132:135], v[140:143], v[32:47]
	ds_read_b128 v[132:135], v128 offset:41536
	s_waitcnt lgkmcnt(0)
	v_mfma_f32_32x32x16_bf16 v[16:31], v[132:135], v[136:139], v[16:31]
	v_mfma_f32_32x32x16_bf16 v[0:15], v[132:135], v[140:143], v[0:15]
	ds_read_b128 v[132:135], v128 offset:36960
	ds_read_b128 v[136:139], v129 offset:55392
	ds_read_b128 v[140:143], v129 offset:60000
	s_waitcnt lgkmcnt(1)
	v_mfma_f32_32x32x16_bf16 v[48:63], v[132:135], v[136:139], v[48:63]
	s_waitcnt lgkmcnt(0)
	v_mfma_f32_32x32x16_bf16 v[32:47], v[132:135], v[140:143], v[32:47]
	ds_read_b128 v[132:135], v128 offset:41568
	s_setprio 0
	s_waitcnt vmcnt(15)
	ds_write_b128 v130, v[92:95]
	s_waitcnt vmcnt(14)
	ds_write_b128 v130, v[64:67] offset:4608
	s_waitcnt vmcnt(13)
	ds_write_b128 v130, v[68:71] offset:9216
	s_waitcnt vmcnt(12)
	ds_write_b128 v130, v[84:87] offset:13824
	s_waitcnt vmcnt(11)
	ds_write_b128 v130, v[72:75] offset:18432
	s_waitcnt vmcnt(10)
	ds_write_b128 v130, v[76:79] offset:23040
	s_waitcnt vmcnt(9)
	ds_write_b128 v130, v[80:83] offset:27648
	s_waitcnt vmcnt(8)
	ds_write_b128 v130, v[88:91] offset:32256
	s_waitcnt lgkmcnt(0)
	s_barrier
; DI int crow(int i, int h) { return (i & 3) + 8 * (i >> 2) + 4 * h; }
; DI void gemm_128_deep(const bf16_t* __restrict__ A, int lda, const bf16_t* __restrict__ B, int ldb, int K, f32x16 (&acc)[2][2], bf16_t* sA, bf16_t* sBunused) {
;     ...
;   MMA_TILE(1)
;   ST_LDS(0, pa0, pa1, pa2, pa3, pb0, pb1, pb2, pb3)
;   __syncthreads();
;   MMA_TILE(0)
;   ST_LDS(1, qa0, qa1, qa2, qa3, qb0, qb1, qb2, qb3)
;   __syncthreads();
;   MMA_TILE(1)
;   __syncthreads();
; DI void phase_out(CP p, const Ptrs& w, int l, bf16_t* sA, bf16_t* sB) {
;     ...
;     int b = m0 / TPB, ib = m0 - b * TPB;
;     bool isctx = ib < CTXL;
;     f32x16 acc[2][2];
;     zero_acc(acc);
;     gemm_128_deep(w.R2 + (size_t)m0 * 2048, 2048, out_t + (size_t)n0 * 2048, 2048, 2048, acc, sA, sB);
;     const float* gate = w.mod + (l * 3 + (isctx ? 2 : b)) * 6144 + 4096;
; #pragma unroll
;     for (int mi = 0; mi < 2; ++mi)
; #pragma unroll
;       for (int ni = 0; ni < 2; ++ni) {
;         int col = n0 + wn * 64 + ni * 32 + r;
;         float gt = gate[col];
; #pragma unroll
;         for (int i = 0; i < 16; ++i) {
;           int ii = ib + wm * 64 + mi * 32 + crow(i, h);
;           const float* src = xrow(p, w, l, b * TPB + ii);
	s_setprio 1
	ds_read_b128 v[64:67], v128
	ds_read_b128 v[68:71], v129 offset:18432
	ds_read_b128 v[72:75], v129 offset:23040
	s_waitcnt lgkmcnt(1)
	v_mfma_f32_32x32x16_bf16 v[48:63], v[64:67], v[68:71], v[48:63]
	v_add_u32_e32 v92, s10, v163
	s_mov_b64 s[10:11], -1
	s_waitcnt lgkmcnt(0)
	v_mfma_f32_32x32x16_bf16 v[32:47], v[64:67], v[72:75], v[32:47]
	ds_read_b128 v[64:67], v128 offset:4608
	v_mfma_f32_32x32x16_bf16 v[16:31], v[132:135], v[136:139], v[16:31]
	v_mfma_f32_32x32x16_bf16 v[0:15], v[132:135], v[140:143], v[0:15]
	s_waitcnt lgkmcnt(0)
	v_mfma_f32_32x32x16_bf16 v[16:31], v[64:67], v[68:71], v[16:31]
	v_mfma_f32_32x32x16_bf16 v[0:15], v[64:67], v[72:75], v[0:15]
	ds_read_b128 v[64:67], v128 offset:32
	ds_read_b128 v[68:71], v129 offset:18464
	ds_read_b128 v[72:75], v129 offset:23072
	s_waitcnt lgkmcnt(1)
	v_mfma_f32_32x32x16_bf16 v[48:63], v[64:67], v[68:71], v[48:63]
	s_waitcnt lgkmcnt(0)
	v_mfma_f32_32x32x16_bf16 v[32:47], v[64:67], v[72:75], v[32:47]
	ds_read_b128 v[64:67], v128 offset:4640
	s_waitcnt lgkmcnt(0)
	v_mfma_f32_32x32x16_bf16 v[16:31], v[64:67], v[68:71], v[16:31]
	v_mfma_f32_32x32x16_bf16 v[0:15], v[64:67], v[72:75], v[0:15]
	ds_read_b128 v[64:67], v128 offset:64
	ds_read_b128 v[68:71], v129 offset:18496
	ds_read_b128 v[72:75], v129 offset:23104
	s_waitcnt lgkmcnt(1)
	v_mfma_f32_32x32x16_bf16 v[48:63], v[64:67], v[68:71], v[48:63]
	s_waitcnt lgkmcnt(0)
	v_mfma_f32_32x32x16_bf16 v[32:47], v[64:67], v[72:75], v[32:47]
	ds_read_b128 v[64:67], v128 offset:4672
	s_waitcnt lgkmcnt(0)
	v_mfma_f32_32x32x16_bf16 v[16:31], v[64:67], v[68:71], v[16:31]
	v_mfma_f32_32x32x16_bf16 v[0:15], v[64:67], v[72:75], v[0:15]
	ds_read_b128 v[64:67], v128 offset:96
	ds_read_b128 v[68:71], v129 offset:18528
	ds_read_b128 v[72:75], v129 offset:23136
	s_waitcnt lgkmcnt(1)
	v_mfma_f32_32x32x16_bf16 v[48:63], v[64:67], v[68:71], v[48:63]
	s_waitcnt lgkmcnt(0)
	v_mfma_f32_32x32x16_bf16 v[32:47], v[64:67], v[72:75], v[32:47]
	ds_read_b128 v[64:67], v128 offset:4704
	s_setprio 0
	s_waitcnt vmcnt(7)
	ds_write_b128 v130, v[96:99] offset:36864
	s_waitcnt vmcnt(6)
	ds_write_b128 v130, v[100:103] offset:41472
	s_waitcnt vmcnt(5)
	ds_write_b128 v130, v[104:107] offset:46080
	s_waitcnt vmcnt(4)
	ds_write_b128 v130, v[108:111] offset:50688
	s_waitcnt vmcnt(3)
	ds_write_b128 v130, v[112:115] offset:55296
	s_waitcnt vmcnt(2)
	ds_write_b128 v130, v[116:119] offset:59904
	s_waitcnt vmcnt(1)
	ds_write_b128 v130, v[120:123] offset:64512
	s_waitcnt vmcnt(0)
	ds_write_b128 v131, v[124:127] offset:13824
	s_waitcnt lgkmcnt(0)
	s_barrier
	s_setprio 1
	v_mfma_f32_32x32x16_bf16 v[16:31], v[64:67], v[68:71], v[16:31]
	v_mfma_f32_32x32x16_bf16 v[0:15], v[64:67], v[72:75], v[0:15]
	ds_read_b128 v[64:67], v128 offset:36864
	ds_read_b128 v[68:71], v129 offset:55296
	ds_read_b128 v[72:75], v129 offset:59904
	s_waitcnt lgkmcnt(1)
	v_mfma_f32_32x32x16_bf16 v[48:63], v[64:67], v[68:71], v[48:63]
	s_waitcnt lgkmcnt(0)
	v_mfma_f32_32x32x16_bf16 v[32:47], v[64:67], v[72:75], v[32:47]
	ds_read_b128 v[64:67], v128 offset:41472
	s_waitcnt lgkmcnt(0)
	v_mfma_f32_32x32x16_bf16 v[16:31], v[64:67], v[68:71], v[16:31]
	v_mfma_f32_32x32x16_bf16 v[0:15], v[64:67], v[72:75], v[0:15]
	ds_read_b128 v[64:67], v128 offset:36896
	ds_read_b128 v[68:71], v129 offset:55328
	ds_read_b128 v[72:75], v129 offset:59936
	s_waitcnt lgkmcnt(1)
	v_mfma_f32_32x32x16_bf16 v[48:63], v[64:67], v[68:71], v[48:63]
	s_waitcnt lgkmcnt(0)
	v_mfma_f32_32x32x16_bf16 v[32:47], v[64:67], v[72:75], v[32:47]
	ds_read_b128 v[64:67], v128 offset:41504
	s_waitcnt lgkmcnt(0)
	v_mfma_f32_32x32x16_bf16 v[16:31], v[64:67], v[68:71], v[16:31]
	v_mfma_f32_32x32x16_bf16 v[0:15], v[64:67], v[72:75], v[0:15]
	ds_read_b128 v[64:67], v128 offset:36928
	ds_read_b128 v[68:71], v129 offset:55360
	ds_read_b128 v[72:75], v129 offset:59968
	s_waitcnt lgkmcnt(1)
	v_mfma_f32_32x32x16_bf16 v[48:63], v[64:67], v[68:71], v[48:63]
	s_waitcnt lgkmcnt(0)
	v_mfma_f32_32x32x16_bf16 v[32:47], v[64:67], v[72:75], v[32:47]
	ds_read_b128 v[64:67], v128 offset:41536
	s_waitcnt lgkmcnt(0)
	v_mfma_f32_32x32x16_bf16 v[16:31], v[64:67], v[68:71], v[16:31]
	ds_read_b128 v[68:71], v128 offset:36960
	ds_read_b128 v[76:79], v128 offset:41568
	ds_read_b128 v[80:83], v129 offset:55392
	ds_read_b128 v[84:87], v129 offset:60000
	s_waitcnt lgkmcnt(0)
	s_barrier
	s_setprio 1
	v_mfma_f32_32x32x16_bf16 v[0:15], v[64:67], v[72:75], v[0:15]
	v_or_b32_e32 v64, s46, v161
	v_ashrrev_i32_e32 v65, 31, v64
	v_or_b32_e32 v72, v92, v164
	v_add_u32_e32 v66, s38, v72
	v_mul_hi_i32 v67, v66, s0
	v_mfma_f32_32x32x16_bf16 v[48:63], v[68:71], v[80:83], v[48:63]
	v_mfma_f32_32x32x16_bf16 v[32:47], v[68:71], v[84:87], v[32:47]
	v_lshl_add_u64 v[68:69], v[64:65], 2, s[6:7]
	global_load_dword v90, v[68:69], off
	v_lshrrev_b32_e32 v70, 31, v67
	v_ashrrev_i32_e32 v67, 11, v67
	v_add_u32_e32 v93, v67, v70
	v_mad_i32_i24 v94, v93, s1, v66
	v_cmp_lt_i32_e64 s[42:43], s37, v94
	v_mfma_f32_32x32x16_bf16 v[16:31], v[76:79], v[80:83], v[16:31]
	v_mfma_f32_32x32x16_bf16 v[0:15], v[76:79], v[84:87], v[0:15]
	s_setprio 0
	s_cbranch_vccz .LBB0_961
	s_and_saveexec_b64 s[10:11], s[42:43]
	s_xor_b64 s[10:11], exec, s[10:11]
	v_lshlrev_b32_e32 v66, 13, v93
	s_movk_i32 s40, 0xff00
	v_add3_u32 v66, v66, v94, s40
	s_or_saveexec_b64 s[10:11], s[10:11]
	v_mov_b64_e32 v[70:71], s[76:77]
	s_xor_b64 exec, exec, s[10:11]
	v_lshl_add_u32 v66, v93, 8, v94
	v_mov_b64_e32 v[70:71], s[12:13]
	s_or_b64 exec, exec, s[10:11]
	s_mov_b64 s[10:11], 0
